# rw_scan staging rewritten (fewer VALU ops, negation folded into multiplies), y row/offset tracked incrementally
# speedup vs baseline: 1.0476x; 1.0035x over previous
.LBB0_768:
	s_lshl_b32 s0, s8, 5
	s_and_b32 s0, s0, 0xe0
	s_ashr_i32 s11, s8, 3
	s_add_i32 s0, s0, s11
	s_bfe_u32 s9, s0, 0x40003
	s_lshl_b32 s6, s9, 8
	v_lshl_add_u64 v[0:1], v[52:53], 0, s[6:7]
	v_lshl_add_u64 v[4:5], v[54:55], 0, s[6:7]
	global_load_dwordx4 v[0:3], v[0:1], off
	s_bfe_u32 s6, s11, 0x10002
	global_load_dwordx4 v[4:7], v[4:5], off
	s_ashr_i32 s12, s0, 7
	s_cmp_eq_u32 s6, 0
	s_cselect_b64 s[46:47], -1, 0
	s_and_saveexec_b64 s[0:1], s[36:37]
	s_xor_b64 s[0:1], exec, s[0:1]
	v_cndmask_b32_e64 v8, v59, v51, s[46:47]
	s_lshl_b32 s10, s12, 13
	s_lshl_b32 s13, s12, 8
	v_add_u32_e32 v8, s10, v8
	v_mov_b32_e32 v10, s13
	v_mov_b32_e32 v98, s10
	s_or_saveexec_b64 s[0:1], s[0:1]
	s_lshl_b32 s10, s9, 6
	s_xor_b64 exec, exec, s[0:1]
	v_cndmask_b32_e64 v8, v71, v49, s[46:47]
	s_lshl_b32 s13, s12, 8
	v_add_u32_e32 v8, s13, v8
	s_lshl_b32 s12, s12, 13
	v_add_u32_e32 v8, 0x4000, v8
	v_mov_b32_e32 v10, s13
	v_mov_b32_e32 v98, s12
	s_or_b64 exec, exec, s[0:1]
	v_mov_b32_e32 v131, v8
	s_lshl_b32 s0, s6, 5
	s_sub_i32 s0, 16, s0
	v_mov_b32_e32 v132, s0
	v_sub_u32_e32 v133, 0x1fff, v49
	v_cndmask_b32_e64 v133, v133, v49, s[46:47]
	v_add_u32_e32 v133, v98, v133
	s_lshl_b32 s0, s9, 2
	v_mov_b32_e32 v134, s0
	s_mul_i32 s6, s6, 0x2100000
	v_ashrrev_i32_e32 v9, 31, v8
	s_add_u32 s24, s86, s6
	v_or_b32_e32 v58, s10, v50
	v_lshlrev_b64 v[12:13], 11, v[8:9]
	s_addc_u32 s25, s87, 0
	v_readlane_b32 s0, v182, 23
	v_lshl_or_b32 v14, v58, 1, v12
	v_mov_b32_e32 v15, v13
	v_readlane_b32 s1, v182, 24
	s_add_u32 s20, s0, s6
	v_lshl_add_u64 v[16:17], s[2:3], 0, v[14:15]
	v_lshl_or_b32 v8, v8, 4, s9
	s_addc_u32 s21, s1, 0
	global_load_dwordx2 v[16:17], v[16:17], off
	v_ashrrev_i32_e32 v9, 31, v8
	v_lshl_add_u64 v[18:19], s[90:91], 0, v[14:15]
	v_lshl_add_u64 v[20:21], s[20:21], 0, v[14:15]
	v_lshl_add_u64 v[14:15], s[24:25], 0, v[14:15]
	v_lshl_add_u64 v[8:9], v[8:9], 2, s[74:75]
	global_load_dwordx2 v[18:19], v[18:19], off
	s_add_u32 vcc_lo, s22, s6
	global_load_dwordx2 v[22:23], v[14:15], off
	v_readlane_b32 s12, v181, 42
	global_load_dword v8, v[8:9], off
	s_addc_u32 vcc_hi, s23, 0
	global_load_dwordx2 v[20:21], v[20:21], off
	s_lshl_b32 s0, s11, 4
	v_readlane_b32 s13, v181, 43
	s_and_b32 s11, s0, 48
	s_lshl_b32 s6, s10, 1
	v_lshl_add_u64 v[12:13], s[12:13], 0, v[12:13]
	v_lshl_add_u64 v[12:13], v[12:13], 0, s[6:7]
	s_lshl_b32 s0, s11, 1
	s_mov_b32 s1, s7
	v_lshl_add_u64 v[12:13], v[12:13], 0, s[0:1]
	v_lshl_add_u64 v[24:25], v[12:13], 0, v[68:69]
	s_add_i32 s10, s10, s11
	s_add_u32 s1, s12, s6
	s_addc_u32 s6, s13, 0
	s_add_u32 s0, s1, s0
	s_addc_u32 s1, s6, 0
	v_lshl_add_u64 v[60:61], s[0:1], 0, v[68:69]
	v_add_u32_e32 v99, 0x4000, v10
	s_mov_b32 s6, 0
	v_mov_b32_e32 v100, v97
	v_mov_b32_e32 v101, v96
	s_waitcnt vmcnt(4)
	v_lshlrev_b32_e32 v26, 16, v16
	v_and_b32_e32 v27, 0xffff0000, v16
	v_pk_mul_f32 v[12:13], v[0:1], v[26:27]
	s_waitcnt vmcnt(2)
	v_alignbit_b32 v11, v23, v22, 16
	s_waitcnt vmcnt(1)
	v_pk_mul_f32 v[30:31], v[12:13], v[8:9] op_sel_hi:[1,0]
	v_alignbit_b32 v9, v17, v16, 16
	v_and_b32_e32 v17, 0xffff0000, v17
	v_and_b32_e32 v16, 0xffff0000, v9
	v_pk_mul_f32 v[14:15], v[2:3], v[16:17]
	v_xor_b32_e32 v13, 0x80000000, v31
	v_pk_mul_f32 v[8:9], v[8:9], v[14:15] op_sel_hi:[0,1]
	v_xor_b32_e32 v12, 0x80000000, v30
	v_xor_b32_e32 v15, 0x80000000, v9
	v_xor_b32_e32 v14, 0x80000000, v8
	ds_write_b128 v81, v[12:15]
	v_lshlrev_b32_e32 v12, 16, v22
	v_and_b32_e32 v13, 0xffff0000, v22
	v_and_b32_e32 v15, 0xffff0000, v23
	v_and_b32_e32 v14, 0xffff0000, v11
	s_waitcnt vmcnt(0)
	v_alignbit_b32 v11, v21, v20, 16
	v_lshlrev_b32_e32 v28, 16, v20
	v_and_b32_e32 v29, 0xffff0000, v20
	v_pk_add_f32 v[12:13], v[12:13], 1.0 op_sel_hi:[1,0] neg_lo:[1,0] neg_hi:[1,0]
	v_pk_add_f32 v[14:15], v[14:15], 1.0 op_sel_hi:[1,0] neg_lo:[1,0] neg_hi:[1,0]
	v_and_b32_e32 v21, 0xffff0000, v21
	v_and_b32_e32 v20, 0xffff0000, v11
	ds_write_b128 v81, v[12:15] offset:256
	v_pk_mul_f32 v[14:15], v[8:9], v[20:21]
	v_pk_add_f32 v[8:9], v[28:29], -1.0 op_sel_hi:[1,0]
	v_pk_mul_f32 v[12:13], v[30:31], v[28:29]
	v_pk_fma_f32 v[8:9], v[4:5], v[8:9], 1.0 op_sel_hi:[1,1,0]
	ds_write_b128 v81, v[12:15] offset:512
	v_pk_mul_f32 v[12:13], v[8:9], v[26:27]
	v_pk_add_f32 v[8:9], v[20:21], -1.0 op_sel_hi:[1,0]
	s_nop 0
	v_pk_fma_f32 v[8:9], v[6:7], v[8:9], 1.0 op_sel_hi:[1,1,0]
	s_nop 0
	v_pk_mul_f32 v[14:15], v[8:9], v[16:17]
	v_alignbit_b32 v8, v19, v18, 16
	ds_write_b128 v81, v[12:15] offset:768
	v_and_b32_e32 v14, 0xffff0000, v8
	global_load_ushort v8, v[24:25], off
	v_and_b32_e32 v15, 0xffff0000, v19
	v_lshlrev_b32_e32 v12, 16, v18
	v_and_b32_e32 v13, 0xffff0000, v18
	ds_write_b128 v81, v[12:15] offset:1024
	s_waitcnt vmcnt(0)
	v_lshlrev_b32_e32 v8, 16, v8
	ds_write_b32 v88, v8 offset:1280
	v_add_u32_e32 v8, s10, v89
	v_ashrrev_i32_e32 v9, 31, v8
	v_lshl_add_u64 v[56:57], v[8:9], 1, vcc
	v_mov_b32_e32 v8, 0
	s_mov_b32 s10, 0
	v_mov_b32_e32 v9, v8
	v_mov_b32_e32 v10, v8
	v_mov_b32_e32 v11, v8
	v_lshlrev_b32_e32 v58, 1, v58
	v_readlane_b32 s100, v181, 42
	v_readlane_b32 s101, v181, 43
	v_sub_u32_e32 v12, 0xff, v48
	v_cndmask_b32_e64 v12, v12, v48, s[46:47]
	v_add_u32_e32 v100, v99, v12
	v_sub_u32_e32 v12, 0x1fff, v48
	v_cndmask_b32_e64 v12, v12, v48, s[46:47]
	v_add_u32_e32 v101, v98, v12
	v_subrev_u32_e32 v60, s100, v60
	v_subrev_u32_e32 v99, s100, v56
	s_waitcnt lgkmcnt(0)
	s_barrier
	s_branch .LBB0_774

.Lscan_top_nox:
	s_and_b32 s11, s10, 1
	v_lshl_add_u32 v13, v131, 11, v58
	v_lshl_add_u32 v14, v131, 6, v134
	v_lshl_add_u32 v15, v131, 11, v60
	s_mul_i32 s0, s11, 0x5400
	global_load_dwordx2 v[74:75], v13, s[2:3]
	global_load_dwordx2 v[62:63], v13, s[90:91]
	global_load_dwordx2 v[76:77], v13, s[24:25]
	global_load_dword v78, v14, s[74:75]
	global_load_dwordx2 v[72:73], v13, s[20:21]
	global_load_ushort v102, v15, s[100:101]
	s_add_i32 s0, s0, 16
	v_lshl_add_u32 v126, v87, 2, s0
	v_add3_u32 v124, s0, v91, v92
	ds_read_b32 v204, v124 offset:1280
	ds_read_b128 v[184:187], v126 offset:0
	ds_read_b128 v[196:199], v126 offset:768
	ds_read_b128 v[188:191], v126 offset:256
	ds_read_b128 v[200:203], v126 offset:1024
	ds_read_b128 v[192:195], v126 offset:512
	ds_read_b32 v226, v124 offset:2624
	ds_read_b128 v[206:209], v126 offset:1344
	ds_read_b128 v[218:221], v126 offset:2112
	ds_read_b128 v[210:213], v126 offset:1600
	ds_read_b128 v[222:225], v126 offset:2368
	ds_read_b128 v[214:217], v126 offset:1856
	s_waitcnt lgkmcnt(6)
	v_pk_mul_f32 v[250:251], v[8:9], v[184:185]
	v_pk_mul_f32 v[252:253], v[204:205], v[196:197] op_sel_hi:[0,1]
	v_pk_fma_f32 v[250:251], v[10:11], v[186:187], v[250:251]
	v_pk_mul_f32 v[254:255], v[204:205], v[198:199] op_sel_hi:[0,1]
	v_add_f32_e32 v14, v250, v251
	v_pk_fma_f32 v[252:253], v[8:9], v[188:189], v[252:253]
	v_pk_fma_f32 v[254:255], v[10:11], v[190:191], v[254:255]
	v_add_f32_dpp v14, v14, v14 quad_perm:[1,0,3,2] row_mask:0xf bank_mask:0xf bound_ctrl:1
	ds_read_b32 v248, v124 offset:3968
	ds_read_b128 v[228:231], v126 offset:2688
	v_add_f32_dpp v14, v14, v14 quad_perm:[2,3,0,1] row_mask:0xf bank_mask:0xf bound_ctrl:1
	ds_read_b128 v[240:243], v126 offset:3456
	ds_read_b128 v[232:235], v126 offset:2944
	v_add_f32_dpp v14, v14, v14 row_half_mirror row_mask:0xf bank_mask:0xf bound_ctrl:1
	ds_read_b128 v[244:247], v126 offset:3712
	ds_read_b128 v[236:239], v126 offset:3200
	v_add_f32_dpp v14, v14, v14 row_mirror row_mask:0xf bank_mask:0xf bound_ctrl:1
	v_pk_fma_f32 v[8:9], v[14:15], v[192:193], v[252:253] op_sel_hi:[0,1,1]
	v_pk_fma_f32 v[10:11], v[14:15], v[194:195], v[254:255] op_sel_hi:[0,1,1]
	s_waitcnt lgkmcnt(6)
	v_pk_mul_f32 v[250:251], v[8:9], v[206:207]
	v_pk_mul_f32 v[252:253], v[226:227], v[218:219] op_sel_hi:[0,1]
	v_pk_fma_f32 v[250:251], v[10:11], v[208:209], v[250:251]
	v_pk_mul_f32 v[254:255], v[226:227], v[220:221] op_sel_hi:[0,1]
	v_add_f32_e32 v14, v250, v251
	v_pk_fma_f32 v[252:253], v[8:9], v[210:211], v[252:253]
	v_pk_fma_f32 v[254:255], v[10:11], v[212:213], v[254:255]
	v_add_f32_dpp v14, v14, v14 quad_perm:[1,0,3,2] row_mask:0xf bank_mask:0xf bound_ctrl:1
	v_pk_mul_f32 v[12:13], v[8:9], v[200:201]
	ds_read_b32 v204, v124 offset:5312
	v_add_f32_dpp v14, v14, v14 quad_perm:[2,3,0,1] row_mask:0xf bank_mask:0xf bound_ctrl:1
	v_pk_fma_f32 v[12:13], v[10:11], v[202:203], v[12:13]
	ds_read_b128 v[184:187], v126 offset:4032
	v_add_f32_dpp v14, v14, v14 row_half_mirror row_mask:0xf bank_mask:0xf bound_ctrl:1
	v_add_f32_e32 v18, v12, v13
	ds_read_b128 v[196:199], v126 offset:4800
	v_add_f32_dpp v14, v14, v14 row_mirror row_mask:0xf bank_mask:0xf bound_ctrl:1
	v_pk_fma_f32 v[8:9], v[14:15], v[214:215], v[252:253] op_sel_hi:[0,1,1]
	v_pk_fma_f32 v[10:11], v[14:15], v[216:217], v[254:255] op_sel_hi:[0,1,1]
	ds_read_b128 v[188:191], v126 offset:4288
	ds_read_b128 v[200:203], v126 offset:5056
	ds_read_b128 v[192:195], v126 offset:4544
	s_waitcnt lgkmcnt(6)
	v_pk_mul_f32 v[250:251], v[8:9], v[228:229]
	v_pk_mul_f32 v[252:253], v[248:249], v[240:241] op_sel_hi:[0,1]
	v_pk_fma_f32 v[250:251], v[10:11], v[230:231], v[250:251]
	v_pk_mul_f32 v[254:255], v[248:249], v[242:243] op_sel_hi:[0,1]
	v_add_f32_e32 v14, v250, v251
	v_pk_fma_f32 v[252:253], v[8:9], v[232:233], v[252:253]
	v_pk_fma_f32 v[254:255], v[10:11], v[234:235], v[254:255]
	v_add_f32_dpp v14, v14, v14 quad_perm:[1,0,3,2] row_mask:0xf bank_mask:0xf bound_ctrl:1
	v_pk_mul_f32 v[12:13], v[8:9], v[222:223]
	ds_read_b32 v226, v124 offset:6656
	v_add_f32_dpp v14, v14, v14 quad_perm:[2,3,0,1] row_mask:0xf bank_mask:0xf bound_ctrl:1
	v_pk_fma_f32 v[12:13], v[10:11], v[224:225], v[12:13]
	ds_read_b128 v[206:209], v126 offset:5376
	v_add_f32_dpp v14, v14, v14 row_half_mirror row_mask:0xf bank_mask:0xf bound_ctrl:1
	v_add_f32_e32 v19, v12, v13
	ds_read_b128 v[218:221], v126 offset:6144
	v_add_f32_dpp v14, v14, v14 row_mirror row_mask:0xf bank_mask:0xf bound_ctrl:1
	v_pk_fma_f32 v[8:9], v[14:15], v[236:237], v[252:253] op_sel_hi:[0,1,1]
	v_pk_fma_f32 v[10:11], v[14:15], v[238:239], v[254:255] op_sel_hi:[0,1,1]
	ds_read_b128 v[210:213], v126 offset:5632
	ds_read_b128 v[222:225], v126 offset:6400
	ds_read_b128 v[214:217], v126 offset:5888
	s_waitcnt lgkmcnt(6)
	v_pk_mul_f32 v[250:251], v[8:9], v[184:185]
	v_pk_mul_f32 v[252:253], v[204:205], v[196:197] op_sel_hi:[0,1]
	v_pk_fma_f32 v[250:251], v[10:11], v[186:187], v[250:251]
	v_pk_mul_f32 v[254:255], v[204:205], v[198:199] op_sel_hi:[0,1]
	v_add_f32_e32 v14, v250, v251
	v_pk_fma_f32 v[252:253], v[8:9], v[188:189], v[252:253]
	v_pk_fma_f32 v[254:255], v[10:11], v[190:191], v[254:255]
	v_add_f32_dpp v14, v14, v14 quad_perm:[1,0,3,2] row_mask:0xf bank_mask:0xf bound_ctrl:1
	v_pk_mul_f32 v[12:13], v[8:9], v[244:245]
	ds_read_b32 v248, v124 offset:8000
	v_add_f32_dpp v14, v14, v14 quad_perm:[2,3,0,1] row_mask:0xf bank_mask:0xf bound_ctrl:1
	v_pk_fma_f32 v[12:13], v[10:11], v[246:247], v[12:13]
	ds_read_b128 v[228:231], v126 offset:6720
	v_add_f32_dpp v14, v14, v14 row_half_mirror row_mask:0xf bank_mask:0xf bound_ctrl:1
	v_add_f32_e32 v20, v12, v13
	ds_read_b128 v[240:243], v126 offset:7488
	v_add_f32_dpp v14, v14, v14 row_mirror row_mask:0xf bank_mask:0xf bound_ctrl:1
	v_pk_fma_f32 v[8:9], v[14:15], v[192:193], v[252:253] op_sel_hi:[0,1,1]
	v_pk_fma_f32 v[10:11], v[14:15], v[194:195], v[254:255] op_sel_hi:[0,1,1]
	ds_read_b128 v[232:235], v126 offset:6976
	ds_read_b128 v[244:247], v126 offset:7744
	ds_read_b128 v[236:239], v126 offset:7232
	s_waitcnt lgkmcnt(6)
	v_pk_mul_f32 v[250:251], v[8:9], v[206:207]
	v_pk_mul_f32 v[252:253], v[226:227], v[218:219] op_sel_hi:[0,1]
	v_pk_fma_f32 v[250:251], v[10:11], v[208:209], v[250:251]
	v_pk_mul_f32 v[254:255], v[226:227], v[220:221] op_sel_hi:[0,1]
	v_add_f32_e32 v14, v250, v251
	v_pk_fma_f32 v[252:253], v[8:9], v[210:211], v[252:253]
	v_pk_fma_f32 v[254:255], v[10:11], v[212:213], v[254:255]
	v_add_f32_dpp v14, v14, v14 quad_perm:[1,0,3,2] row_mask:0xf bank_mask:0xf bound_ctrl:1
	v_pk_mul_f32 v[12:13], v[8:9], v[200:201]
	ds_read_b32 v204, v124 offset:9344
	v_add_f32_dpp v14, v14, v14 quad_perm:[2,3,0,1] row_mask:0xf bank_mask:0xf bound_ctrl:1
	v_pk_fma_f32 v[12:13], v[10:11], v[202:203], v[12:13]
	ds_read_b128 v[184:187], v126 offset:8064
	v_add_f32_dpp v14, v14, v14 row_half_mirror row_mask:0xf bank_mask:0xf bound_ctrl:1
	v_add_f32_e32 v21, v12, v13
	ds_read_b128 v[196:199], v126 offset:8832
	v_add_f32_dpp v14, v14, v14 row_mirror row_mask:0xf bank_mask:0xf bound_ctrl:1
	v_pk_fma_f32 v[8:9], v[14:15], v[214:215], v[252:253] op_sel_hi:[0,1,1]
	v_pk_fma_f32 v[10:11], v[14:15], v[216:217], v[254:255] op_sel_hi:[0,1,1]
	ds_read_b128 v[188:191], v126 offset:8320
	ds_read_b128 v[200:203], v126 offset:9088
	ds_read_b128 v[192:195], v126 offset:8576
	s_waitcnt lgkmcnt(6)
	v_pk_mul_f32 v[250:251], v[8:9], v[228:229]
	v_pk_mul_f32 v[252:253], v[248:249], v[240:241] op_sel_hi:[0,1]
	v_pk_fma_f32 v[250:251], v[10:11], v[230:231], v[250:251]
	v_pk_mul_f32 v[254:255], v[248:249], v[242:243] op_sel_hi:[0,1]
	v_add_f32_e32 v14, v250, v251
	v_pk_fma_f32 v[252:253], v[8:9], v[232:233], v[252:253]
	v_pk_fma_f32 v[254:255], v[10:11], v[234:235], v[254:255]
	v_add_f32_dpp v14, v14, v14 quad_perm:[1,0,3,2] row_mask:0xf bank_mask:0xf bound_ctrl:1
	v_pk_mul_f32 v[12:13], v[8:9], v[222:223]
	ds_read_b32 v226, v124 offset:10688
	v_add_f32_dpp v14, v14, v14 quad_perm:[2,3,0,1] row_mask:0xf bank_mask:0xf bound_ctrl:1
	v_pk_fma_f32 v[12:13], v[10:11], v[224:225], v[12:13]
	ds_read_b128 v[206:209], v126 offset:9408
	v_add_f32_dpp v14, v14, v14 row_half_mirror row_mask:0xf bank_mask:0xf bound_ctrl:1
	v_add_f32_e32 v22, v12, v13
	ds_read_b128 v[218:221], v126 offset:10176
	v_add_f32_dpp v14, v14, v14 row_mirror row_mask:0xf bank_mask:0xf bound_ctrl:1
	v_pk_fma_f32 v[8:9], v[14:15], v[236:237], v[252:253] op_sel_hi:[0,1,1]
	v_pk_fma_f32 v[10:11], v[14:15], v[238:239], v[254:255] op_sel_hi:[0,1,1]
	ds_read_b128 v[210:213], v126 offset:9664
	ds_read_b128 v[222:225], v126 offset:10432
	ds_read_b128 v[214:217], v126 offset:9920
	s_waitcnt lgkmcnt(6)
	v_pk_mul_f32 v[250:251], v[8:9], v[184:185]
	v_pk_mul_f32 v[252:253], v[204:205], v[196:197] op_sel_hi:[0,1]
	v_pk_fma_f32 v[250:251], v[10:11], v[186:187], v[250:251]
	v_pk_mul_f32 v[254:255], v[204:205], v[198:199] op_sel_hi:[0,1]
	v_add_f32_e32 v14, v250, v251
	v_pk_fma_f32 v[252:253], v[8:9], v[188:189], v[252:253]
	v_pk_fma_f32 v[254:255], v[10:11], v[190:191], v[254:255]
	v_add_f32_dpp v14, v14, v14 quad_perm:[1,0,3,2] row_mask:0xf bank_mask:0xf bound_ctrl:1
	v_pk_mul_f32 v[12:13], v[8:9], v[244:245]
	ds_read_b32 v248, v124 offset:12032
	v_add_f32_dpp v14, v14, v14 quad_perm:[2,3,0,1] row_mask:0xf bank_mask:0xf bound_ctrl:1
	v_pk_fma_f32 v[12:13], v[10:11], v[246:247], v[12:13]
	ds_read_b128 v[228:231], v126 offset:10752
	v_add_f32_dpp v14, v14, v14 row_half_mirror row_mask:0xf bank_mask:0xf bound_ctrl:1
	v_add_f32_e32 v23, v12, v13
	ds_read_b128 v[240:243], v126 offset:11520
	v_add_f32_dpp v14, v14, v14 row_mirror row_mask:0xf bank_mask:0xf bound_ctrl:1
	v_pk_fma_f32 v[8:9], v[14:15], v[192:193], v[252:253] op_sel_hi:[0,1,1]
	v_pk_fma_f32 v[10:11], v[14:15], v[194:195], v[254:255] op_sel_hi:[0,1,1]
	ds_read_b128 v[232:235], v126 offset:11008
	ds_read_b128 v[244:247], v126 offset:11776
	ds_read_b128 v[236:239], v126 offset:11264
	s_waitcnt lgkmcnt(6)
	v_pk_mul_f32 v[250:251], v[8:9], v[206:207]
	v_pk_mul_f32 v[252:253], v[226:227], v[218:219] op_sel_hi:[0,1]
	v_pk_fma_f32 v[250:251], v[10:11], v[208:209], v[250:251]
	v_pk_mul_f32 v[254:255], v[226:227], v[220:221] op_sel_hi:[0,1]
	v_add_f32_e32 v14, v250, v251
	v_pk_fma_f32 v[252:253], v[8:9], v[210:211], v[252:253]
	v_pk_fma_f32 v[254:255], v[10:11], v[212:213], v[254:255]
	v_add_f32_dpp v14, v14, v14 quad_perm:[1,0,3,2] row_mask:0xf bank_mask:0xf bound_ctrl:1
	v_pk_mul_f32 v[12:13], v[8:9], v[200:201]
	ds_read_b32 v204, v124 offset:13376
	v_add_f32_dpp v14, v14, v14 quad_perm:[2,3,0,1] row_mask:0xf bank_mask:0xf bound_ctrl:1
	v_pk_fma_f32 v[12:13], v[10:11], v[202:203], v[12:13]
	ds_read_b128 v[184:187], v126 offset:12096
	v_add_f32_dpp v14, v14, v14 row_half_mirror row_mask:0xf bank_mask:0xf bound_ctrl:1
	v_add_f32_e32 v24, v12, v13
	ds_read_b128 v[196:199], v126 offset:12864
	v_add_f32_dpp v14, v14, v14 row_mirror row_mask:0xf bank_mask:0xf bound_ctrl:1
	v_pk_fma_f32 v[8:9], v[14:15], v[214:215], v[252:253] op_sel_hi:[0,1,1]
	v_pk_fma_f32 v[10:11], v[14:15], v[216:217], v[254:255] op_sel_hi:[0,1,1]
	ds_read_b128 v[188:191], v126 offset:12352
	ds_read_b128 v[200:203], v126 offset:13120
	ds_read_b128 v[192:195], v126 offset:12608
	s_waitcnt lgkmcnt(6)
	v_pk_mul_f32 v[250:251], v[8:9], v[228:229]
	v_pk_mul_f32 v[252:253], v[248:249], v[240:241] op_sel_hi:[0,1]
	v_pk_fma_f32 v[250:251], v[10:11], v[230:231], v[250:251]
	v_pk_mul_f32 v[254:255], v[248:249], v[242:243] op_sel_hi:[0,1]
	v_add_f32_e32 v14, v250, v251
	v_pk_fma_f32 v[252:253], v[8:9], v[232:233], v[252:253]
	v_pk_fma_f32 v[254:255], v[10:11], v[234:235], v[254:255]
	v_add_f32_dpp v14, v14, v14 quad_perm:[1,0,3,2] row_mask:0xf bank_mask:0xf bound_ctrl:1
	v_pk_mul_f32 v[12:13], v[8:9], v[222:223]
	ds_read_b32 v226, v124 offset:14720
	v_add_f32_dpp v14, v14, v14 quad_perm:[2,3,0,1] row_mask:0xf bank_mask:0xf bound_ctrl:1
	v_pk_fma_f32 v[12:13], v[10:11], v[224:225], v[12:13]
	ds_read_b128 v[206:209], v126 offset:13440
	v_add_f32_dpp v14, v14, v14 row_half_mirror row_mask:0xf bank_mask:0xf bound_ctrl:1
	v_add_f32_e32 v25, v12, v13
	ds_read_b128 v[218:221], v126 offset:14208
	v_add_f32_dpp v14, v14, v14 row_mirror row_mask:0xf bank_mask:0xf bound_ctrl:1
	v_pk_fma_f32 v[8:9], v[14:15], v[236:237], v[252:253] op_sel_hi:[0,1,1]
	v_pk_fma_f32 v[10:11], v[14:15], v[238:239], v[254:255] op_sel_hi:[0,1,1]
	ds_read_b128 v[210:213], v126 offset:13696
	ds_read_b128 v[222:225], v126 offset:14464
	ds_read_b128 v[214:217], v126 offset:13952
	s_waitcnt vmcnt(0)
	s_xor_b32 s0, s11, 1
	s_mulk_i32 s0, 0x5400
	v_add_u32_e32 v82, s0, v79
	v_lshlrev_b32_e32 v34, 16, v74
	v_and_b32_e32 v35, 0xffff0000, v74
	v_lshlrev_b32_e32 v36, 16, v75
	v_and_b32_e32 v37, 0xffff0000, v75
	v_lshl_add_u32 v83, v50, 2, v82
	v_pk_mul_f32 v[38:39], v[0:1], v[34:35]
	v_pk_mul_f32 v[40:41], v[2:3], v[36:37]
	v_lshlrev_b32_e32 v120, 16, v72
	v_pk_mul_f32 v[42:43], v[78:79], v[38:39] op_sel_hi:[0,1] neg_lo:[1,0] neg_hi:[1,0]
	v_pk_mul_f32 v[44:45], v[78:79], v[40:41] op_sel_hi:[0,1] neg_lo:[1,0] neg_hi:[1,0]
	v_and_b32_e32 v121, 0xffff0000, v72
	v_lshlrev_b32_e32 v122, 16, v73
	v_and_b32_e32 v123, 0xffff0000, v73
	ds_write_b128 v83, v[42:45]
	v_lshlrev_b32_e32 v38, 16, v76
	v_and_b32_e32 v39, 0xffff0000, v76
	v_lshlrev_b32_e32 v40, 16, v77
	v_and_b32_e32 v41, 0xffff0000, v77
	v_pk_add_f32 v[38:39], v[38:39], 1.0 op_sel_hi:[1,0] neg_lo:[1,0] neg_hi:[1,0]
	v_pk_add_f32 v[40:41], v[40:41], 1.0 op_sel_hi:[1,0] neg_lo:[1,0] neg_hi:[1,0]
	v_lshl_add_u32 v85, v48, 2, v82
	ds_write_b128 v83, v[38:41] offset:256
	v_pk_mul_f32 v[38:39], v[42:43], v[120:121] neg_lo:[1,0] neg_hi:[1,0]
	v_pk_mul_f32 v[40:41], v[44:45], v[122:123] neg_lo:[1,0] neg_hi:[1,0]
	v_pk_add_f32 v[120:121], v[120:121], -1.0 op_sel_hi:[1,0]
	v_pk_add_f32 v[122:123], v[122:123], -1.0 op_sel_hi:[1,0]
	ds_write_b128 v83, v[38:41] offset:512
	v_pk_fma_f32 v[120:121], v[4:5], v[120:121], 1.0 op_sel_hi:[1,1,0]
	v_pk_fma_f32 v[122:123], v[6:7], v[122:123], 1.0 op_sel_hi:[1,1,0]
	v_lshlrev_b32_e32 v42, 16, v62
	v_and_b32_e32 v43, 0xffff0000, v62
	v_pk_mul_f32 v[120:121], v[120:121], v[34:35]
	v_pk_mul_f32 v[122:123], v[122:123], v[36:37]
	v_lshlrev_b32_e32 v44, 16, v63
	v_and_b32_e32 v45, 0xffff0000, v63
	v_lshlrev_b32_e32 v84, 16, v102
	ds_write_b128 v83, v[120:123] offset:768
	ds_write_b128 v83, v[42:45] offset:1024
	ds_write_b32 v85, v84 offset:1280
	s_waitcnt lgkmcnt(12)
	v_pk_mul_f32 v[250:251], v[8:9], v[184:185]
	v_pk_mul_f32 v[252:253], v[204:205], v[196:197] op_sel_hi:[0,1]
	v_pk_fma_f32 v[250:251], v[10:11], v[186:187], v[250:251]
	v_pk_mul_f32 v[254:255], v[204:205], v[198:199] op_sel_hi:[0,1]
	v_add_f32_e32 v14, v250, v251
	v_pk_fma_f32 v[252:253], v[8:9], v[188:189], v[252:253]
	v_pk_fma_f32 v[254:255], v[10:11], v[190:191], v[254:255]
	v_add_f32_dpp v14, v14, v14 quad_perm:[1,0,3,2] row_mask:0xf bank_mask:0xf bound_ctrl:1
	v_pk_mul_f32 v[12:13], v[8:9], v[244:245]
	ds_read_b32 v248, v124 offset:16064
	v_add_f32_dpp v14, v14, v14 quad_perm:[2,3,0,1] row_mask:0xf bank_mask:0xf bound_ctrl:1
	v_pk_fma_f32 v[12:13], v[10:11], v[246:247], v[12:13]
	ds_read_b128 v[228:231], v126 offset:14784
	v_add_f32_dpp v14, v14, v14 row_half_mirror row_mask:0xf bank_mask:0xf bound_ctrl:1
	v_add_f32_e32 v26, v12, v13
	ds_read_b128 v[240:243], v126 offset:15552
	v_add_f32_dpp v14, v14, v14 row_mirror row_mask:0xf bank_mask:0xf bound_ctrl:1
	v_pk_fma_f32 v[8:9], v[14:15], v[192:193], v[252:253] op_sel_hi:[0,1,1]
	v_pk_fma_f32 v[10:11], v[14:15], v[194:195], v[254:255] op_sel_hi:[0,1,1]
	ds_read_b128 v[232:235], v126 offset:15040
	ds_read_b128 v[244:247], v126 offset:15808
	ds_read_b128 v[236:239], v126 offset:15296
	s_waitcnt lgkmcnt(12)
	v_pk_mul_f32 v[250:251], v[8:9], v[206:207]
	v_pk_mul_f32 v[252:253], v[226:227], v[218:219] op_sel_hi:[0,1]
	v_pk_fma_f32 v[250:251], v[10:11], v[208:209], v[250:251]
	v_pk_mul_f32 v[254:255], v[226:227], v[220:221] op_sel_hi:[0,1]
	v_add_f32_e32 v14, v250, v251
	v_pk_fma_f32 v[252:253], v[8:9], v[210:211], v[252:253]
	v_pk_fma_f32 v[254:255], v[10:11], v[212:213], v[254:255]
	v_add_f32_dpp v14, v14, v14 quad_perm:[1,0,3,2] row_mask:0xf bank_mask:0xf bound_ctrl:1
	v_pk_mul_f32 v[12:13], v[8:9], v[200:201]
	ds_read_b32 v204, v124 offset:17408
	v_add_f32_dpp v14, v14, v14 quad_perm:[2,3,0,1] row_mask:0xf bank_mask:0xf bound_ctrl:1
	v_pk_fma_f32 v[12:13], v[10:11], v[202:203], v[12:13]
	ds_read_b128 v[184:187], v126 offset:16128
	v_add_f32_dpp v14, v14, v14 row_half_mirror row_mask:0xf bank_mask:0xf bound_ctrl:1
	v_add_f32_e32 v27, v12, v13
	ds_read_b128 v[196:199], v126 offset:16896
	v_add_f32_dpp v14, v14, v14 row_mirror row_mask:0xf bank_mask:0xf bound_ctrl:1
	v_pk_fma_f32 v[8:9], v[14:15], v[214:215], v[252:253] op_sel_hi:[0,1,1]
	v_pk_fma_f32 v[10:11], v[14:15], v[216:217], v[254:255] op_sel_hi:[0,1,1]
	ds_read_b128 v[188:191], v126 offset:16384
	ds_read_b128 v[200:203], v126 offset:17152
	ds_read_b128 v[192:195], v126 offset:16640
	s_waitcnt lgkmcnt(6)
	v_pk_mul_f32 v[250:251], v[8:9], v[228:229]
	v_pk_mul_f32 v[252:253], v[248:249], v[240:241] op_sel_hi:[0,1]
	v_pk_fma_f32 v[250:251], v[10:11], v[230:231], v[250:251]
	v_pk_mul_f32 v[254:255], v[248:249], v[242:243] op_sel_hi:[0,1]
	v_add_f32_e32 v14, v250, v251
	v_pk_fma_f32 v[252:253], v[8:9], v[232:233], v[252:253]
	v_pk_fma_f32 v[254:255], v[10:11], v[234:235], v[254:255]
	v_add_f32_dpp v14, v14, v14 quad_perm:[1,0,3,2] row_mask:0xf bank_mask:0xf bound_ctrl:1
	v_pk_mul_f32 v[12:13], v[8:9], v[222:223]
	ds_read_b32 v226, v124 offset:18752
	v_add_f32_dpp v14, v14, v14 quad_perm:[2,3,0,1] row_mask:0xf bank_mask:0xf bound_ctrl:1
	v_pk_fma_f32 v[12:13], v[10:11], v[224:225], v[12:13]
	ds_read_b128 v[206:209], v126 offset:17472
	v_add_f32_dpp v14, v14, v14 row_half_mirror row_mask:0xf bank_mask:0xf bound_ctrl:1
	v_add_f32_e32 v28, v12, v13
	ds_read_b128 v[218:221], v126 offset:18240
	v_add_f32_dpp v14, v14, v14 row_mirror row_mask:0xf bank_mask:0xf bound_ctrl:1
	v_pk_fma_f32 v[8:9], v[14:15], v[236:237], v[252:253] op_sel_hi:[0,1,1]
	v_pk_fma_f32 v[10:11], v[14:15], v[238:239], v[254:255] op_sel_hi:[0,1,1]
	ds_read_b128 v[210:213], v126 offset:17728
	ds_read_b128 v[222:225], v126 offset:18496
	ds_read_b128 v[214:217], v126 offset:17984
	s_waitcnt lgkmcnt(6)
	v_pk_mul_f32 v[250:251], v[8:9], v[184:185]
	v_pk_mul_f32 v[252:253], v[204:205], v[196:197] op_sel_hi:[0,1]
	v_pk_fma_f32 v[250:251], v[10:11], v[186:187], v[250:251]
	v_pk_mul_f32 v[254:255], v[204:205], v[198:199] op_sel_hi:[0,1]
	v_add_f32_e32 v14, v250, v251
	v_pk_fma_f32 v[252:253], v[8:9], v[188:189], v[252:253]
	v_pk_fma_f32 v[254:255], v[10:11], v[190:191], v[254:255]
	v_add_f32_dpp v14, v14, v14 quad_perm:[1,0,3,2] row_mask:0xf bank_mask:0xf bound_ctrl:1
	v_pk_mul_f32 v[12:13], v[8:9], v[244:245]
	ds_read_b32 v248, v124 offset:20096
	v_add_f32_dpp v14, v14, v14 quad_perm:[2,3,0,1] row_mask:0xf bank_mask:0xf bound_ctrl:1
	v_pk_fma_f32 v[12:13], v[10:11], v[246:247], v[12:13]
	ds_read_b128 v[228:231], v126 offset:18816
	v_add_f32_dpp v14, v14, v14 row_half_mirror row_mask:0xf bank_mask:0xf bound_ctrl:1
	v_add_f32_e32 v29, v12, v13
	ds_read_b128 v[240:243], v126 offset:19584
	v_add_f32_dpp v14, v14, v14 row_mirror row_mask:0xf bank_mask:0xf bound_ctrl:1
	v_pk_fma_f32 v[8:9], v[14:15], v[192:193], v[252:253] op_sel_hi:[0,1,1]
	v_pk_fma_f32 v[10:11], v[14:15], v[194:195], v[254:255] op_sel_hi:[0,1,1]
	ds_read_b128 v[232:235], v126 offset:19072
	ds_read_b128 v[244:247], v126 offset:19840
	ds_read_b128 v[236:239], v126 offset:19328
	s_waitcnt lgkmcnt(6)
	v_pk_mul_f32 v[250:251], v[8:9], v[206:207]
	v_pk_mul_f32 v[252:253], v[226:227], v[218:219] op_sel_hi:[0,1]
	v_pk_fma_f32 v[250:251], v[10:11], v[208:209], v[250:251]
	v_pk_mul_f32 v[254:255], v[226:227], v[220:221] op_sel_hi:[0,1]
	v_add_f32_e32 v14, v250, v251
	v_pk_fma_f32 v[252:253], v[8:9], v[210:211], v[252:253]
	v_pk_fma_f32 v[254:255], v[10:11], v[212:213], v[254:255]
	v_add_f32_dpp v14, v14, v14 quad_perm:[1,0,3,2] row_mask:0xf bank_mask:0xf bound_ctrl:1
	v_pk_mul_f32 v[12:13], v[8:9], v[200:201]
	ds_read_b32 v204, v124 offset:21440
	v_add_f32_dpp v14, v14, v14 quad_perm:[2,3,0,1] row_mask:0xf bank_mask:0xf bound_ctrl:1
	v_pk_fma_f32 v[12:13], v[10:11], v[202:203], v[12:13]
	ds_read_b128 v[184:187], v126 offset:20160
	v_add_f32_dpp v14, v14, v14 row_half_mirror row_mask:0xf bank_mask:0xf bound_ctrl:1
	v_add_f32_e32 v30, v12, v13
	ds_read_b128 v[196:199], v126 offset:20928
	v_add_f32_dpp v14, v14, v14 row_mirror row_mask:0xf bank_mask:0xf bound_ctrl:1
	v_pk_fma_f32 v[8:9], v[14:15], v[214:215], v[252:253] op_sel_hi:[0,1,1]
	v_pk_fma_f32 v[10:11], v[14:15], v[216:217], v[254:255] op_sel_hi:[0,1,1]
	ds_read_b128 v[188:191], v126 offset:20416
	ds_read_b128 v[200:203], v126 offset:21184
	ds_read_b128 v[192:195], v126 offset:20672
	s_waitcnt lgkmcnt(6)
	v_pk_mul_f32 v[250:251], v[8:9], v[228:229]
	v_pk_mul_f32 v[252:253], v[248:249], v[240:241] op_sel_hi:[0,1]
	v_pk_fma_f32 v[250:251], v[10:11], v[230:231], v[250:251]
	v_pk_mul_f32 v[254:255], v[248:249], v[242:243] op_sel_hi:[0,1]
	v_add_f32_e32 v14, v250, v251
	v_pk_fma_f32 v[252:253], v[8:9], v[232:233], v[252:253]
	v_pk_fma_f32 v[254:255], v[10:11], v[234:235], v[254:255]
	v_add_f32_dpp v14, v14, v14 quad_perm:[1,0,3,2] row_mask:0xf bank_mask:0xf bound_ctrl:1
	v_pk_mul_f32 v[12:13], v[8:9], v[222:223]
	s_nop 0
	v_add_f32_dpp v14, v14, v14 quad_perm:[2,3,0,1] row_mask:0xf bank_mask:0xf bound_ctrl:1
	v_pk_fma_f32 v[12:13], v[10:11], v[224:225], v[12:13]
	s_nop 0
	v_add_f32_dpp v14, v14, v14 row_half_mirror row_mask:0xf bank_mask:0xf bound_ctrl:1
	v_add_f32_e32 v31, v12, v13
	s_nop 0
	v_add_f32_dpp v14, v14, v14 row_mirror row_mask:0xf bank_mask:0xf bound_ctrl:1
	v_pk_fma_f32 v[8:9], v[14:15], v[236:237], v[252:253] op_sel_hi:[0,1,1]
	v_pk_fma_f32 v[10:11], v[14:15], v[238:239], v[254:255] op_sel_hi:[0,1,1]
	s_waitcnt lgkmcnt(0)
	v_pk_mul_f32 v[250:251], v[8:9], v[184:185]
	v_pk_mul_f32 v[252:253], v[204:205], v[196:197] op_sel_hi:[0,1]
	v_pk_fma_f32 v[250:251], v[10:11], v[186:187], v[250:251]
	v_pk_mul_f32 v[254:255], v[204:205], v[198:199] op_sel_hi:[0,1]
	v_add_f32_e32 v14, v250, v251
	v_pk_fma_f32 v[252:253], v[8:9], v[188:189], v[252:253]
	v_pk_fma_f32 v[254:255], v[10:11], v[190:191], v[254:255]
	v_add_f32_dpp v14, v14, v14 quad_perm:[1,0,3,2] row_mask:0xf bank_mask:0xf bound_ctrl:1
	v_pk_mul_f32 v[12:13], v[8:9], v[244:245]
	s_nop 0
	v_add_f32_dpp v14, v14, v14 quad_perm:[2,3,0,1] row_mask:0xf bank_mask:0xf bound_ctrl:1
	v_pk_fma_f32 v[12:13], v[10:11], v[246:247], v[12:13]
	s_nop 0
	v_add_f32_dpp v14, v14, v14 row_half_mirror row_mask:0xf bank_mask:0xf bound_ctrl:1
	v_add_f32_e32 v32, v12, v13
	s_nop 0
	v_add_f32_dpp v14, v14, v14 row_mirror row_mask:0xf bank_mask:0xf bound_ctrl:1
	v_pk_fma_f32 v[8:9], v[14:15], v[192:193], v[252:253] op_sel_hi:[0,1,1]
	v_pk_fma_f32 v[10:11], v[14:15], v[194:195], v[254:255] op_sel_hi:[0,1,1]
	v_pk_mul_f32 v[12:13], v[8:9], v[200:201]
	v_add_f32_dpp v34, v18, v18 row_mirror row_mask:0xf bank_mask:0x3 bound_ctrl:1
	v_pk_fma_f32 v[12:13], v[10:11], v[202:203], v[12:13]
	v_add_f32_dpp v35, v19, v19 row_mirror row_mask:0xf bank_mask:0x3 bound_ctrl:1
	v_add_f32_dpp v36, v20, v20 row_mirror row_mask:0xf bank_mask:0x3 bound_ctrl:1
	v_add_f32_e32 v33, v12, v13
	v_add_f32_dpp v37, v21, v21 row_mirror row_mask:0xf bank_mask:0x3 bound_ctrl:1
	v_add_f32_dpp v38, v22, v22 row_mirror row_mask:0xf bank_mask:0x3 bound_ctrl:1
	v_add_f32_dpp v39, v23, v23 row_mirror row_mask:0xf bank_mask:0x3 bound_ctrl:1
	v_add_f32_dpp v40, v24, v24 row_mirror row_mask:0xf bank_mask:0x3 bound_ctrl:1
	v_add_f32_dpp v41, v25, v25 row_mirror row_mask:0xf bank_mask:0x3 bound_ctrl:1
	v_add_f32_dpp v34, v26, v26 row_mirror row_mask:0xf bank_mask:0xc bound_ctrl:1
	v_add_f32_dpp v35, v27, v27 row_mirror row_mask:0xf bank_mask:0xc bound_ctrl:1
	v_add_f32_dpp v36, v28, v28 row_mirror row_mask:0xf bank_mask:0xc bound_ctrl:1
	v_add_f32_dpp v37, v29, v29 row_mirror row_mask:0xf bank_mask:0xc bound_ctrl:1
	v_add_f32_dpp v38, v30, v30 row_mirror row_mask:0xf bank_mask:0xc bound_ctrl:1
	v_add_f32_dpp v39, v31, v31 row_mirror row_mask:0xf bank_mask:0xc bound_ctrl:1
	v_add_f32_dpp v40, v32, v32 row_mirror row_mask:0xf bank_mask:0xc bound_ctrl:1
	v_add_f32_dpp v41, v33, v33 row_mirror row_mask:0xf bank_mask:0xc bound_ctrl:1
	v_add_f32_dpp v42, v34, v34 row_half_mirror row_mask:0xf bank_mask:0x5 bound_ctrl:1
	v_add_f32_dpp v43, v35, v35 row_half_mirror row_mask:0xf bank_mask:0x5 bound_ctrl:1
	v_add_f32_dpp v44, v36, v36 row_half_mirror row_mask:0xf bank_mask:0x5 bound_ctrl:1
	v_add_f32_dpp v45, v37, v37 row_half_mirror row_mask:0xf bank_mask:0x5 bound_ctrl:1
	v_add_f32_dpp v42, v38, v38 row_half_mirror row_mask:0xf bank_mask:0xa bound_ctrl:1
	v_add_f32_dpp v43, v39, v39 row_half_mirror row_mask:0xf bank_mask:0xa bound_ctrl:1
	v_add_f32_dpp v44, v40, v40 row_half_mirror row_mask:0xf bank_mask:0xa bound_ctrl:1
	v_add_f32_dpp v45, v41, v41 row_half_mirror row_mask:0xf bank_mask:0xa bound_ctrl:1
	v_cndmask_b32_e64 v80, v44, v42, s[42:43]
	v_cndmask_b32_e64 v121, v42, v44, s[42:43]
	v_cndmask_b32_e64 v82, v45, v43, s[42:43]
	v_cndmask_b32_e64 v122, v43, v45, s[42:43]
	s_nop 0
	s_nop 0
	v_add_f32_dpp v13, v121, v80 quad_perm:[2,3,0,1] row_mask:0xf bank_mask:0xf bound_ctrl:1
	v_add_f32_dpp v14, v122, v82 quad_perm:[2,3,0,1] row_mask:0xf bank_mask:0xf bound_ctrl:1
	v_cndmask_b32_e64 v12, v13, v14, s[44:45]
	v_cndmask_b32_e64 v13, v14, v13, s[44:45]
	v_lshl_add_u32 v16, v100, 11, v99
	v_add_u32_e32 v100, v132, v100
	v_add_f32_dpp v13, v12, v13 quad_perm:[1,0,3,2] row_mask:0xf bank_mask:0xf bound_ctrl:1
	s_cmp_eq_u32 s10, 15
	s_cbranch_scc0 .Lscan_tail_nox
	v_mov_b32_e32 v100, v101
.Lscan_tail_nox:
	v_cvt_pk_bf16_f32 v14, v13, v13
	global_store_short v16, v14, s[100:101]
	s_add_i32 s6, s6, 16
	s_add_i32 s10, s10, 1
	s_cmpk_eq_i32 s6, 0x20f0
	s_waitcnt lgkmcnt(0)
	s_barrier
	s_cbranch_scc1 .LBB0_767
	s_branch .LBB0_774
